# counted waits: attention step head vmcnt(5), prep loop tail vmcnt(8); sync spin cap raised
# speedup vs baseline: 1.0156x; 1.0013x over previous
.LBB0_693:
	s_xor_b64 s[24:25], s[8:9], -1
	s_add_i32 s4, s53, 1
	s_cmp_lg_u32 s53, 23
	s_waitcnt vmcnt(5)
	v_mov_b64_e32 v[34:35], v[50:51]
	v_mov_b64_e32 v[38:39], v[54:55]
	v_mov_b64_e32 v[42:43], v[58:59]
	v_mov_b64_e32 v[46:47], v[62:63]
	s_cselect_b64 s[96:97], -1, 0
	s_cmp_eq_u32 s53, 23
	v_mov_b64_e32 v[36:37], v[52:53]
	v_mov_b64_e32 v[40:41], v[56:57]
	v_mov_b64_e32 v[44:45], v[60:61]
	v_mov_b64_e32 v[48:49], v[64:65]
	s_cbranch_scc1 .LBB0_703
	s_cmp_gt_u32 s53, 6
	s_mov_b64 s[8:9], -1
	s_cbranch_scc0 .LBB0_700
	s_cmp_gt_u32 s53, 14
	s_cbranch_scc0 .LBB0_697
	s_add_i32 s8, s53, -15
	s_lshr_b32 s8, s8, 1
	v_readlane_b32 s9, v255, 8
	s_add_i32 s31, s8, s9
	s_and_b32 s30, s4, 1
	s_mov_b64 s[8:9], 0

.LBB0_836:
	s_andn2_saveexec_b64 s[8:9], s[18:19]
	s_cbranch_execz .LBB0_807
	s_cmp_eq_u32 s20, 0x7f0000
	s_cbranch_scc1 .LBB0_807
	s_add_u32 s100, s100, 4
	v_mov_b32_e32 v42, 0x21f00
	v_mov_b32_e32 v43, 1
	s_mov_b64 s[18:19], exec
	s_mov_b64 exec, 1
	ds_add_u32 v42, v43
	s_mov_b64 exec, s[18:19]
	s_mov_b32 s101, 0x400000

.LBB0_873:
	v_mov_b64_e32 v[100:101], v[104:105]
	v_mov_b64_e32 v[102:103], v[106:107]
	v_mov_b64_e32 v[104:105], v[112:113]
	v_mov_b64_e32 v[106:107], v[114:115]
	v_mov_b64_e32 v[112:113], v[132:133]
	v_mov_b64_e32 v[114:115], v[134:135]
	v_mov_b64_e32 v[132:133], v[144:145]
	s_waitcnt vmcnt(8)
	v_mov_b64_e32 v[108:109], v[116:117]
	s_and_b64 vcc, exec, s[8:9]
	v_mov_b64_e32 v[134:135], v[146:147]
	v_mov_b64_e32 v[212:213], v[196:197]
	v_mov_b64_e32 v[208:209], v[192:193]
	v_mov_b64_e32 v[204:205], v[188:189]
	v_mov_b64_e32 v[200:201], v[184:185]
	v_mov_b64_e32 v[214:215], v[198:199]
	v_mov_b64_e32 v[210:211], v[194:195]
	v_mov_b64_e32 v[206:207], v[190:191]
	v_mov_b64_e32 v[202:203], v[186:187]
	s_mov_b32 s5, s4
	v_mov_b64_e32 v[110:111], v[118:119]
	v_mov_b32_e32 v144, v128
	v_mov_b32_e32 v145, v129
	v_mov_b32_e32 v146, v130
	v_mov_b32_e32 v147, v131
	v_mov_b32_e32 v140, v124
	v_mov_b32_e32 v141, v125
	v_mov_b32_e32 v142, v126
	v_mov_b32_e32 v143, v127
	v_mov_b32_e32 v136, v120
	v_mov_b32_e32 v137, v121
	v_mov_b32_e32 v138, v122
	v_mov_b32_e32 v139, v123
	v_mov_b32_e32 v216, v116
	v_mov_b32_e32 v217, v117
	v_mov_b32_e32 v218, v118
	v_mov_b32_e32 v219, v119
	s_cbranch_vccnz .LBB0_895
